# K-loop: per-phase s_setprio flips replaced by one static s_setprio 1 for the trailing half (waves 4-7) during the K loop, reset to 0 at loop exit
# speedup vs baseline: 1.0072x; 1.0072x over previous
.Lno_restore:
	v_readlane_b32 s82, v255, 33
	s_cmp_lg_u32 s82, 0
	s_cbranch_scc1 .Lprio_done
	s_setprio 1
.Lprio_done:
	s_add_u32 s0, s90, 0x80
	s_addc_u32 s1, s91, 0
	s_add_u32 s11, s2, 0x100
	s_addc_u32 s24, s3, 0
	s_mov_b32 s2, 0
	s_add_i32 s90, s2, 2
	s_add_u32 s82, s0, 0x80
	s_addc_u32 s3, s1, 0
	s_add_i32 s83, 0, 0x10000
	s_cmp_eq_u32 s62, s2
	s_cselect_b32 s3, s23, s3
	s_cselect_b32 s2, s22, s82
	s_cselect_b32 vcc_hi, s13, s24
	s_cselect_b32 vcc_lo, s12, s11
	s_add_i32 s82, 0, 0x14000
	v_add_u32_e32 v140, s83, v157
	v_add_u32_e32 v144, s82, v157
	ds_read_b128 v[128:131], v140
	ds_read_b128 v[132:135], v140 offset:1024
	ds_read_b128 v[136:139], v140 offset:2048
	ds_read_b128 v[140:143], v140 offset:3072
	ds_read_b128 v[166:169], v144
	ds_read_b128 v[176:179], v144 offset:1024
	ds_read_b128 v[180:183], v144 offset:2048
	ds_read_b128 v[184:187], v144 offset:3072
	v_lshl_add_u64 v[170:171], s[0:1], 0, v[160:161]
	s_add_i32 m0, s37, 0xc000
	ds_read_b128 v[188:191], v242
	ds_read_b128 v[192:195], v242 offset:1024
	ds_read_b128 v[196:199], v242 offset:2048
	ds_read_b128 v[200:203], v242 offset:3072
	ds_read_b128 v[204:207], v242 offset:4096
	ds_read_b128 v[208:211], v242 offset:5120
	ds_read_b128 v[212:215], v242 offset:6144
	ds_read_b128 v[216:219], v242 offset:7168
	global_load_lds_dwordx4 v[170:171], off
	v_lshl_add_u64 v[170:171], s[0:1], 0, v[162:163]
	s_add_i32 m0, s37, 0xe000
	s_nop 0
	global_load_lds_dwordx4 v[170:171], off
	s_waitcnt vmcnt(8) lgkmcnt(0)
	s_barrier
	v_mfma_f32_16x16x32_bf16 v[124:127], v[128:131], v[188:191], 0
	v_mfma_f32_16x16x32_bf16 v[120:123], v[136:139], v[188:191], 0
	v_mfma_f32_16x16x32_bf16 v[108:111], v[128:131], v[196:199], 0
	v_mfma_f32_16x16x32_bf16 v[104:107], v[136:139], v[196:199], 0
	v_mfma_f32_16x16x32_bf16 v[92:95], v[128:131], v[204:207], 0
	v_mfma_f32_16x16x32_bf16 v[88:91], v[136:139], v[204:207], 0
	v_mfma_f32_16x16x32_bf16 v[76:79], v[128:131], v[212:215], 0
	v_mfma_f32_16x16x32_bf16 v[72:75], v[136:139], v[212:215], 0
	v_mfma_f32_16x16x32_bf16 v[124:127], v[132:135], v[192:195], v[124:127]
	v_mfma_f32_16x16x32_bf16 v[120:123], v[140:143], v[192:195], v[120:123]
	v_mfma_f32_16x16x32_bf16 v[108:111], v[132:135], v[200:203], v[108:111]
	v_mfma_f32_16x16x32_bf16 v[104:107], v[140:143], v[200:203], v[104:107]
	v_mfma_f32_16x16x32_bf16 v[92:95], v[132:135], v[208:211], v[92:95]
	v_mfma_f32_16x16x32_bf16 v[88:91], v[140:143], v[208:211], v[88:91]
	v_mfma_f32_16x16x32_bf16 v[76:79], v[132:135], v[216:219], v[76:79]
	v_mfma_f32_16x16x32_bf16 v[72:75], v[140:143], v[216:219], v[72:75]
	v_mfma_f32_16x16x32_bf16 v[116:119], v[166:169], v[188:191], 0
	v_mfma_f32_16x16x32_bf16 v[112:115], v[180:183], v[188:191], 0
	v_mfma_f32_16x16x32_bf16 v[100:103], v[166:169], v[196:199], 0
	v_mfma_f32_16x16x32_bf16 v[96:99], v[180:183], v[196:199], 0
	v_mfma_f32_16x16x32_bf16 v[84:87], v[166:169], v[204:207], 0
	v_mfma_f32_16x16x32_bf16 v[80:83], v[180:183], v[204:207], 0
	v_mfma_f32_16x16x32_bf16 v[68:71], v[166:169], v[212:215], 0
	v_mfma_f32_16x16x32_bf16 v[64:67], v[180:183], v[212:215], 0
	v_mfma_f32_16x16x32_bf16 v[116:119], v[176:179], v[192:195], v[116:119]
	v_mfma_f32_16x16x32_bf16 v[112:115], v[184:187], v[192:195], v[112:115]
	v_mfma_f32_16x16x32_bf16 v[100:103], v[176:179], v[200:203], v[100:103]
	v_mfma_f32_16x16x32_bf16 v[96:99], v[184:187], v[200:203], v[96:99]
	v_mfma_f32_16x16x32_bf16 v[84:87], v[176:179], v[208:211], v[84:87]
	v_mfma_f32_16x16x32_bf16 v[80:83], v[184:187], v[208:211], v[80:83]
	v_mfma_f32_16x16x32_bf16 v[68:71], v[176:179], v[216:219], v[68:71]
	v_mfma_f32_16x16x32_bf16 v[64:67], v[184:187], v[216:219], v[64:67]
	s_barrier
	s_add_i32 s83, s83, s36
	v_lshl_add_u64 v[170:171], vcc, 0, v[150:151]
	s_mov_b32 m0, s83
	ds_read_b128 v[188:191], v242 offset:16384
	ds_read_b128 v[192:195], v242 offset:17408
	ds_read_b128 v[196:199], v242 offset:18432
	ds_read_b128 v[200:203], v242 offset:19456
	ds_read_b128 v[204:207], v242 offset:20480
	ds_read_b128 v[208:211], v242 offset:21504
	ds_read_b128 v[212:215], v242 offset:22528
	ds_read_b128 v[216:219], v242 offset:23552
	global_load_lds_dwordx4 v[170:171], off
	s_add_i32 m0, s83, 0x2000
	v_lshl_add_u64 v[232:233], vcc, 0, v[154:155]
	s_add_u32 vcc_lo, vcc_lo, s26
	s_addc_u32 vcc_hi, vcc_hi, 0
	s_add_i32 s82, s82, s36
	global_load_lds_dwordx4 v[232:233], off
	v_lshl_add_u64 v[234:235], vcc, 0, v[150:151]
	s_mov_b32 m0, s82
	v_lshl_add_u64 v[246:247], vcc, 0, v[154:155]
	global_load_lds_dwordx4 v[234:235], off
	s_add_i32 m0, s82, 0x2000
	v_lshl_add_u64 v[248:249], s[2:3], 0, v[148:149]
	global_load_lds_dwordx4 v[246:247], off
	s_mov_b32 m0, s37
	v_lshl_add_u64 v[250:251], s[2:3], 0, v[152:153]
	global_load_lds_dwordx4 v[248:249], off
	s_mov_b32 m0, s42
	s_nop 0
	global_load_lds_dwordx4 v[250:251], off
	s_waitcnt vmcnt(8) lgkmcnt(0)
	s_barrier
	v_mfma_f32_16x16x32_bf16 v[60:63], v[128:131], v[188:191], 0
	v_mfma_f32_16x16x32_bf16 v[56:59], v[136:139], v[188:191], 0
	v_mfma_f32_16x16x32_bf16 v[44:47], v[128:131], v[196:199], 0
	v_mfma_f32_16x16x32_bf16 v[40:43], v[136:139], v[196:199], 0
	v_mfma_f32_16x16x32_bf16 v[28:31], v[128:131], v[204:207], 0
	v_mfma_f32_16x16x32_bf16 v[24:27], v[136:139], v[204:207], 0
	v_mfma_f32_16x16x32_bf16 v[12:15], v[128:131], v[212:215], 0
	v_mfma_f32_16x16x32_bf16 v[8:11], v[136:139], v[212:215], 0
	v_mfma_f32_16x16x32_bf16 v[60:63], v[132:135], v[192:195], v[60:63]
	v_mfma_f32_16x16x32_bf16 v[56:59], v[140:143], v[192:195], v[56:59]
	v_mfma_f32_16x16x32_bf16 v[44:47], v[132:135], v[200:203], v[44:47]
	v_mfma_f32_16x16x32_bf16 v[40:43], v[140:143], v[200:203], v[40:43]
	v_mfma_f32_16x16x32_bf16 v[28:31], v[132:135], v[208:211], v[28:31]
	v_mfma_f32_16x16x32_bf16 v[24:27], v[140:143], v[208:211], v[24:27]
	v_mfma_f32_16x16x32_bf16 v[12:15], v[132:135], v[216:219], v[12:15]
	v_mfma_f32_16x16x32_bf16 v[8:11], v[140:143], v[216:219], v[8:11]
	v_mfma_f32_16x16x32_bf16 v[52:55], v[166:169], v[188:191], 0
	v_mfma_f32_16x16x32_bf16 v[48:51], v[180:183], v[188:191], 0
	v_mfma_f32_16x16x32_bf16 v[36:39], v[166:169], v[196:199], 0
	v_mfma_f32_16x16x32_bf16 v[32:35], v[180:183], v[196:199], 0
	v_mfma_f32_16x16x32_bf16 v[20:23], v[166:169], v[204:207], 0
	v_mfma_f32_16x16x32_bf16 v[16:19], v[180:183], v[204:207], 0
	v_mfma_f32_16x16x32_bf16 v[4:7], v[166:169], v[212:215], 0
	v_mfma_f32_16x16x32_bf16 v[0:3], v[180:183], v[212:215], 0
	v_mfma_f32_16x16x32_bf16 v[52:55], v[176:179], v[192:195], v[52:55]
	v_mfma_f32_16x16x32_bf16 v[48:51], v[184:187], v[192:195], v[48:51]
	v_mfma_f32_16x16x32_bf16 v[36:39], v[176:179], v[200:203], v[36:39]
	v_mfma_f32_16x16x32_bf16 v[32:35], v[184:187], v[200:203], v[32:35]
	v_mfma_f32_16x16x32_bf16 v[20:23], v[176:179], v[208:211], v[20:23]
	v_mfma_f32_16x16x32_bf16 v[16:19], v[184:187], v[208:211], v[16:19]
	v_mfma_f32_16x16x32_bf16 v[4:7], v[176:179], v[216:219], v[4:7]
	v_mfma_f32_16x16x32_bf16 v[0:3], v[184:187], v[216:219], v[0:3]
	s_barrier
	s_add_i32 s82, 0, 0x18000
	s_add_i32 s83, 0, 0x1c000
	v_add_u32_e32 v140, s82, v157
	v_add_u32_e32 v144, s83, v157
	ds_read_b128 v[128:131], v140
	ds_read_b128 v[132:135], v140 offset:1024
	ds_read_b128 v[136:139], v140 offset:2048
	ds_read_b128 v[140:143], v140 offset:3072
	ds_read_b128 v[166:169], v144
	ds_read_b128 v[176:179], v144 offset:1024
	ds_read_b128 v[180:183], v144 offset:2048
	ds_read_b128 v[184:187], v144 offset:3072
	s_add_u32 s2, s2, s58
	s_addc_u32 s3, s3, 0
	s_mov_b32 m0, s43
	v_lshl_add_u64 v[238:239], s[2:3], 0, v[148:149]
	ds_read_b128 v[188:191], v242 offset:32768
	ds_read_b128 v[192:195], v242 offset:33792
	ds_read_b128 v[196:199], v242 offset:34816
	ds_read_b128 v[200:203], v242 offset:35840
	ds_read_b128 v[204:207], v242 offset:36864
	ds_read_b128 v[208:211], v242 offset:37888
	ds_read_b128 v[212:215], v242 offset:38912
	ds_read_b128 v[216:219], v242 offset:39936
	global_load_lds_dwordx4 v[238:239], off
	v_lshl_add_u64 v[238:239], s[2:3], 0, v[152:153]
	s_mov_b32 m0, s16
	s_nop 0
	global_load_lds_dwordx4 v[238:239], off
	s_waitcnt vmcnt(8) lgkmcnt(0)
	s_barrier
	v_mfma_f32_16x16x32_bf16 v[124:127], v[128:131], v[188:191], v[124:127]
	v_mfma_f32_16x16x32_bf16 v[120:123], v[136:139], v[188:191], v[120:123]
	v_mfma_f32_16x16x32_bf16 v[108:111], v[128:131], v[196:199], v[108:111]
	v_mfma_f32_16x16x32_bf16 v[104:107], v[136:139], v[196:199], v[104:107]
	v_mfma_f32_16x16x32_bf16 v[92:95], v[128:131], v[204:207], v[92:95]
	v_mfma_f32_16x16x32_bf16 v[88:91], v[136:139], v[204:207], v[88:91]
	v_mfma_f32_16x16x32_bf16 v[76:79], v[128:131], v[212:215], v[76:79]
	v_mfma_f32_16x16x32_bf16 v[72:75], v[136:139], v[212:215], v[72:75]
	v_mfma_f32_16x16x32_bf16 v[124:127], v[132:135], v[192:195], v[124:127]
	v_mfma_f32_16x16x32_bf16 v[120:123], v[140:143], v[192:195], v[120:123]
	v_mfma_f32_16x16x32_bf16 v[108:111], v[132:135], v[200:203], v[108:111]
	v_mfma_f32_16x16x32_bf16 v[104:107], v[140:143], v[200:203], v[104:107]
	v_mfma_f32_16x16x32_bf16 v[92:95], v[132:135], v[208:211], v[92:95]
	v_mfma_f32_16x16x32_bf16 v[88:91], v[140:143], v[208:211], v[88:91]
	v_mfma_f32_16x16x32_bf16 v[76:79], v[132:135], v[216:219], v[76:79]
	v_mfma_f32_16x16x32_bf16 v[72:75], v[140:143], v[216:219], v[72:75]
	v_mfma_f32_16x16x32_bf16 v[116:119], v[166:169], v[188:191], v[116:119]
	v_mfma_f32_16x16x32_bf16 v[112:115], v[180:183], v[188:191], v[112:115]
	v_mfma_f32_16x16x32_bf16 v[100:103], v[166:169], v[196:199], v[100:103]
	v_mfma_f32_16x16x32_bf16 v[96:99], v[180:183], v[196:199], v[96:99]
	v_mfma_f32_16x16x32_bf16 v[84:87], v[166:169], v[204:207], v[84:87]
	v_mfma_f32_16x16x32_bf16 v[80:83], v[180:183], v[204:207], v[80:83]
	v_mfma_f32_16x16x32_bf16 v[68:71], v[166:169], v[212:215], v[68:71]
	v_mfma_f32_16x16x32_bf16 v[64:67], v[180:183], v[212:215], v[64:67]
	v_mfma_f32_16x16x32_bf16 v[116:119], v[176:179], v[192:195], v[116:119]
	v_mfma_f32_16x16x32_bf16 v[112:115], v[184:187], v[192:195], v[112:115]
	v_mfma_f32_16x16x32_bf16 v[100:103], v[176:179], v[200:203], v[100:103]
	v_mfma_f32_16x16x32_bf16 v[96:99], v[184:187], v[200:203], v[96:99]
	v_mfma_f32_16x16x32_bf16 v[84:87], v[176:179], v[208:211], v[84:87]
	v_mfma_f32_16x16x32_bf16 v[80:83], v[184:187], v[208:211], v[80:83]
	v_mfma_f32_16x16x32_bf16 v[68:71], v[176:179], v[216:219], v[68:71]
	v_mfma_f32_16x16x32_bf16 v[64:67], v[184:187], v[216:219], v[64:67]
	s_barrier
	s_add_i32 s2, s82, s36
	v_lshl_add_u64 v[170:171], v[170:171], 0, s[30:31]
	s_mov_b32 m0, s2
	ds_read_b128 v[188:191], v242 offset:49152
	ds_read_b128 v[192:195], v242 offset:50176
	ds_read_b128 v[196:199], v242 offset:51200
	ds_read_b128 v[200:203], v242 offset:52224
	ds_read_b128 v[204:207], v242 offset:53248
	ds_read_b128 v[208:211], v242 offset:54272
	ds_read_b128 v[212:215], v242 offset:55296
	ds_read_b128 v[216:219], v242 offset:56320
	global_load_lds_dwordx4 v[170:171], off
	v_lshl_add_u64 v[170:171], v[232:233], 0, s[30:31]
	s_add_i32 m0, s2, 0x2000
	s_add_i32 s2, s83, s36
	global_load_lds_dwordx4 v[170:171], off
	v_lshl_add_u64 v[170:171], v[234:235], 0, s[30:31]
	s_mov_b32 m0, s2
	s_nop 0
	global_load_lds_dwordx4 v[170:171], off
	v_lshl_add_u64 v[170:171], v[246:247], 0, s[30:31]
	s_add_i32 m0, s2, 0x2000
	s_nop 0
	global_load_lds_dwordx4 v[170:171], off
	v_lshl_add_u64 v[170:171], v[248:249], 0, s[30:31]
	s_mov_b32 m0, s63
	s_nop 0
	global_load_lds_dwordx4 v[170:171], off
	v_lshl_add_u64 v[170:171], v[250:251], 0, s[30:31]
	s_mov_b32 m0, s18
	s_nop 0
	global_load_lds_dwordx4 v[170:171], off
	s_waitcnt vmcnt(8) lgkmcnt(0)
	s_barrier
	v_mfma_f32_16x16x32_bf16 v[60:63], v[128:131], v[188:191], v[60:63]
	v_mfma_f32_16x16x32_bf16 v[56:59], v[136:139], v[188:191], v[56:59]
	v_mfma_f32_16x16x32_bf16 v[44:47], v[128:131], v[196:199], v[44:47]
	v_mfma_f32_16x16x32_bf16 v[40:43], v[136:139], v[196:199], v[40:43]
	v_mfma_f32_16x16x32_bf16 v[28:31], v[128:131], v[204:207], v[28:31]
	v_mfma_f32_16x16x32_bf16 v[24:27], v[136:139], v[204:207], v[24:27]
	v_mfma_f32_16x16x32_bf16 v[12:15], v[128:131], v[212:215], v[12:15]
	v_mfma_f32_16x16x32_bf16 v[8:11], v[136:139], v[212:215], v[8:11]
	v_mfma_f32_16x16x32_bf16 v[60:63], v[132:135], v[192:195], v[60:63]
	v_mfma_f32_16x16x32_bf16 v[56:59], v[140:143], v[192:195], v[56:59]
	v_mfma_f32_16x16x32_bf16 v[44:47], v[132:135], v[200:203], v[44:47]
	v_mfma_f32_16x16x32_bf16 v[40:43], v[140:143], v[200:203], v[40:43]
	v_mfma_f32_16x16x32_bf16 v[28:31], v[132:135], v[208:211], v[28:31]
	v_mfma_f32_16x16x32_bf16 v[24:27], v[140:143], v[208:211], v[24:27]
	v_mfma_f32_16x16x32_bf16 v[12:15], v[132:135], v[216:219], v[12:15]
	v_mfma_f32_16x16x32_bf16 v[8:11], v[140:143], v[216:219], v[8:11]
	v_mfma_f32_16x16x32_bf16 v[52:55], v[166:169], v[188:191], v[52:55]
	v_mfma_f32_16x16x32_bf16 v[48:51], v[180:183], v[188:191], v[48:51]
	v_mfma_f32_16x16x32_bf16 v[36:39], v[166:169], v[196:199], v[36:39]
	v_mfma_f32_16x16x32_bf16 v[32:35], v[180:183], v[196:199], v[32:35]
	v_mfma_f32_16x16x32_bf16 v[20:23], v[166:169], v[204:207], v[20:23]
	v_mfma_f32_16x16x32_bf16 v[16:19], v[180:183], v[204:207], v[16:19]
	v_mfma_f32_16x16x32_bf16 v[4:7], v[166:169], v[212:215], v[4:7]
	v_mfma_f32_16x16x32_bf16 v[0:3], v[180:183], v[212:215], v[0:3]
	v_mfma_f32_16x16x32_bf16 v[52:55], v[176:179], v[192:195], v[52:55]
	v_mfma_f32_16x16x32_bf16 v[48:51], v[184:187], v[192:195], v[48:51]
	v_mfma_f32_16x16x32_bf16 v[36:39], v[176:179], v[200:203], v[36:39]
	v_mfma_f32_16x16x32_bf16 v[32:35], v[184:187], v[200:203], v[32:35]
	v_mfma_f32_16x16x32_bf16 v[20:23], v[176:179], v[208:211], v[20:23]
	v_mfma_f32_16x16x32_bf16 v[16:19], v[184:187], v[208:211], v[16:19]
	v_mfma_f32_16x16x32_bf16 v[4:7], v[176:179], v[216:219], v[4:7]
	v_mfma_f32_16x16x32_bf16 v[0:3], v[184:187], v[216:219], v[0:3]
	s_barrier
	s_add_u32 s0, s0, 0x100
	s_addc_u32 s1, s1, 0
	s_add_u32 s11, s11, 0x100
	s_addc_u32 s24, s24, 0
	s_cmp_ge_u32 s90, s60
	s_mov_b32 s2, s90
	s_cbranch_scc1 .LBB0_297
.LBB0_295:
	s_add_i32 s90, s2, 2
	s_add_u32 s82, s0, 0x80
	s_addc_u32 s3, s1, 0
	s_add_i32 s83, 0, 0x10000
	s_cmp_eq_u32 s62, s2
	s_cselect_b32 s3, s23, s3
	s_cselect_b32 s2, s22, s82
	s_cselect_b32 vcc_hi, s13, s24
	s_cselect_b32 vcc_lo, s12, s11
	s_add_i32 s82, 0, 0x14000
	v_add_u32_e32 v140, s83, v157
	v_add_u32_e32 v144, s82, v157
	ds_read_b128 v[128:131], v140
	ds_read_b128 v[132:135], v140 offset:1024
	ds_read_b128 v[136:139], v140 offset:2048
	ds_read_b128 v[140:143], v140 offset:3072
	ds_read_b128 v[166:169], v144
	ds_read_b128 v[176:179], v144 offset:1024
	ds_read_b128 v[180:183], v144 offset:2048
	ds_read_b128 v[184:187], v144 offset:3072
	v_lshl_add_u64 v[170:171], s[0:1], 0, v[160:161]
	s_add_i32 m0, s37, 0xc000
	ds_read_b128 v[188:191], v242
	ds_read_b128 v[192:195], v242 offset:1024
	ds_read_b128 v[196:199], v242 offset:2048
	ds_read_b128 v[200:203], v242 offset:3072
	ds_read_b128 v[204:207], v242 offset:4096
	ds_read_b128 v[208:211], v242 offset:5120
	ds_read_b128 v[212:215], v242 offset:6144
	ds_read_b128 v[216:219], v242 offset:7168
	global_load_lds_dwordx4 v[170:171], off
	v_lshl_add_u64 v[170:171], s[0:1], 0, v[162:163]
	s_add_i32 m0, s37, 0xe000
	s_nop 0
	global_load_lds_dwordx4 v[170:171], off
	s_waitcnt vmcnt(8) lgkmcnt(0)
	s_barrier
	v_mfma_f32_16x16x32_bf16 v[124:127], v[128:131], v[188:191], v[124:127]
	v_mfma_f32_16x16x32_bf16 v[120:123], v[136:139], v[188:191], v[120:123]
	v_mfma_f32_16x16x32_bf16 v[108:111], v[128:131], v[196:199], v[108:111]
	v_mfma_f32_16x16x32_bf16 v[104:107], v[136:139], v[196:199], v[104:107]
	v_mfma_f32_16x16x32_bf16 v[92:95], v[128:131], v[204:207], v[92:95]
	v_mfma_f32_16x16x32_bf16 v[88:91], v[136:139], v[204:207], v[88:91]
	v_mfma_f32_16x16x32_bf16 v[76:79], v[128:131], v[212:215], v[76:79]
	v_mfma_f32_16x16x32_bf16 v[72:75], v[136:139], v[212:215], v[72:75]
	v_mfma_f32_16x16x32_bf16 v[124:127], v[132:135], v[192:195], v[124:127]
	v_mfma_f32_16x16x32_bf16 v[120:123], v[140:143], v[192:195], v[120:123]
	v_mfma_f32_16x16x32_bf16 v[108:111], v[132:135], v[200:203], v[108:111]
	v_mfma_f32_16x16x32_bf16 v[104:107], v[140:143], v[200:203], v[104:107]
	v_mfma_f32_16x16x32_bf16 v[92:95], v[132:135], v[208:211], v[92:95]
	v_mfma_f32_16x16x32_bf16 v[88:91], v[140:143], v[208:211], v[88:91]
	v_mfma_f32_16x16x32_bf16 v[76:79], v[132:135], v[216:219], v[76:79]
	v_mfma_f32_16x16x32_bf16 v[72:75], v[140:143], v[216:219], v[72:75]
	v_mfma_f32_16x16x32_bf16 v[116:119], v[166:169], v[188:191], v[116:119]
	v_mfma_f32_16x16x32_bf16 v[112:115], v[180:183], v[188:191], v[112:115]
	v_mfma_f32_16x16x32_bf16 v[100:103], v[166:169], v[196:199], v[100:103]
	v_mfma_f32_16x16x32_bf16 v[96:99], v[180:183], v[196:199], v[96:99]
	v_mfma_f32_16x16x32_bf16 v[84:87], v[166:169], v[204:207], v[84:87]
	v_mfma_f32_16x16x32_bf16 v[80:83], v[180:183], v[204:207], v[80:83]
	v_mfma_f32_16x16x32_bf16 v[68:71], v[166:169], v[212:215], v[68:71]
	v_mfma_f32_16x16x32_bf16 v[64:67], v[180:183], v[212:215], v[64:67]
	v_mfma_f32_16x16x32_bf16 v[116:119], v[176:179], v[192:195], v[116:119]
	v_mfma_f32_16x16x32_bf16 v[112:115], v[184:187], v[192:195], v[112:115]
	v_mfma_f32_16x16x32_bf16 v[100:103], v[176:179], v[200:203], v[100:103]
	v_mfma_f32_16x16x32_bf16 v[96:99], v[184:187], v[200:203], v[96:99]
	v_mfma_f32_16x16x32_bf16 v[84:87], v[176:179], v[208:211], v[84:87]
	v_mfma_f32_16x16x32_bf16 v[80:83], v[184:187], v[208:211], v[80:83]
	v_mfma_f32_16x16x32_bf16 v[68:71], v[176:179], v[216:219], v[68:71]
	v_mfma_f32_16x16x32_bf16 v[64:67], v[184:187], v[216:219], v[64:67]
	s_barrier
	s_add_i32 s83, s83, s36
	v_lshl_add_u64 v[170:171], vcc, 0, v[150:151]
	s_mov_b32 m0, s83
	ds_read_b128 v[188:191], v242 offset:16384
	ds_read_b128 v[192:195], v242 offset:17408
	ds_read_b128 v[196:199], v242 offset:18432
	ds_read_b128 v[200:203], v242 offset:19456
	ds_read_b128 v[204:207], v242 offset:20480
	ds_read_b128 v[208:211], v242 offset:21504
	ds_read_b128 v[212:215], v242 offset:22528
	ds_read_b128 v[216:219], v242 offset:23552
	global_load_lds_dwordx4 v[170:171], off
	s_add_i32 m0, s83, 0x2000
	v_lshl_add_u64 v[232:233], vcc, 0, v[154:155]
	s_add_u32 vcc_lo, vcc_lo, s26
	s_addc_u32 vcc_hi, vcc_hi, 0
	s_add_i32 s82, s82, s36
	global_load_lds_dwordx4 v[232:233], off
	v_lshl_add_u64 v[234:235], vcc, 0, v[150:151]
	s_mov_b32 m0, s82
	v_lshl_add_u64 v[246:247], vcc, 0, v[154:155]
	global_load_lds_dwordx4 v[234:235], off
	s_add_i32 m0, s82, 0x2000
	v_lshl_add_u64 v[248:249], s[2:3], 0, v[148:149]
	global_load_lds_dwordx4 v[246:247], off
	s_mov_b32 m0, s37
	v_lshl_add_u64 v[250:251], s[2:3], 0, v[152:153]
	global_load_lds_dwordx4 v[248:249], off
	s_mov_b32 m0, s42
	s_nop 0
	global_load_lds_dwordx4 v[250:251], off
	s_waitcnt vmcnt(8) lgkmcnt(0)
	s_barrier
	v_mfma_f32_16x16x32_bf16 v[60:63], v[128:131], v[188:191], v[60:63]
	v_mfma_f32_16x16x32_bf16 v[56:59], v[136:139], v[188:191], v[56:59]
	v_mfma_f32_16x16x32_bf16 v[44:47], v[128:131], v[196:199], v[44:47]
	v_mfma_f32_16x16x32_bf16 v[40:43], v[136:139], v[196:199], v[40:43]
	v_mfma_f32_16x16x32_bf16 v[28:31], v[128:131], v[204:207], v[28:31]
	v_mfma_f32_16x16x32_bf16 v[24:27], v[136:139], v[204:207], v[24:27]
	v_mfma_f32_16x16x32_bf16 v[12:15], v[128:131], v[212:215], v[12:15]
	v_mfma_f32_16x16x32_bf16 v[8:11], v[136:139], v[212:215], v[8:11]
	v_mfma_f32_16x16x32_bf16 v[60:63], v[132:135], v[192:195], v[60:63]
	v_mfma_f32_16x16x32_bf16 v[56:59], v[140:143], v[192:195], v[56:59]
	v_mfma_f32_16x16x32_bf16 v[44:47], v[132:135], v[200:203], v[44:47]
	v_mfma_f32_16x16x32_bf16 v[40:43], v[140:143], v[200:203], v[40:43]
	v_mfma_f32_16x16x32_bf16 v[28:31], v[132:135], v[208:211], v[28:31]
	v_mfma_f32_16x16x32_bf16 v[24:27], v[140:143], v[208:211], v[24:27]
	v_mfma_f32_16x16x32_bf16 v[12:15], v[132:135], v[216:219], v[12:15]
	v_mfma_f32_16x16x32_bf16 v[8:11], v[140:143], v[216:219], v[8:11]
	v_mfma_f32_16x16x32_bf16 v[52:55], v[166:169], v[188:191], v[52:55]
	v_mfma_f32_16x16x32_bf16 v[48:51], v[180:183], v[188:191], v[48:51]
	v_mfma_f32_16x16x32_bf16 v[36:39], v[166:169], v[196:199], v[36:39]
	v_mfma_f32_16x16x32_bf16 v[32:35], v[180:183], v[196:199], v[32:35]
	v_mfma_f32_16x16x32_bf16 v[20:23], v[166:169], v[204:207], v[20:23]
	v_mfma_f32_16x16x32_bf16 v[16:19], v[180:183], v[204:207], v[16:19]
	v_mfma_f32_16x16x32_bf16 v[4:7], v[166:169], v[212:215], v[4:7]
	v_mfma_f32_16x16x32_bf16 v[0:3], v[180:183], v[212:215], v[0:3]
	v_mfma_f32_16x16x32_bf16 v[52:55], v[176:179], v[192:195], v[52:55]
	v_mfma_f32_16x16x32_bf16 v[48:51], v[184:187], v[192:195], v[48:51]
	v_mfma_f32_16x16x32_bf16 v[36:39], v[176:179], v[200:203], v[36:39]
	v_mfma_f32_16x16x32_bf16 v[32:35], v[184:187], v[200:203], v[32:35]
	v_mfma_f32_16x16x32_bf16 v[20:23], v[176:179], v[208:211], v[20:23]
	v_mfma_f32_16x16x32_bf16 v[16:19], v[184:187], v[208:211], v[16:19]
	v_mfma_f32_16x16x32_bf16 v[4:7], v[176:179], v[216:219], v[4:7]
	v_mfma_f32_16x16x32_bf16 v[0:3], v[184:187], v[216:219], v[0:3]
	s_barrier
	s_add_i32 s82, 0, 0x18000
	s_add_i32 s83, 0, 0x1c000
	v_add_u32_e32 v140, s82, v157
	v_add_u32_e32 v144, s83, v157
	ds_read_b128 v[128:131], v140
	ds_read_b128 v[132:135], v140 offset:1024
	ds_read_b128 v[136:139], v140 offset:2048
	ds_read_b128 v[140:143], v140 offset:3072
	ds_read_b128 v[166:169], v144
	ds_read_b128 v[176:179], v144 offset:1024
	ds_read_b128 v[180:183], v144 offset:2048
	ds_read_b128 v[184:187], v144 offset:3072
	s_add_u32 s2, s2, s58
	s_addc_u32 s3, s3, 0
	s_mov_b32 m0, s43
	v_lshl_add_u64 v[238:239], s[2:3], 0, v[148:149]
	ds_read_b128 v[188:191], v242 offset:32768
	ds_read_b128 v[192:195], v242 offset:33792
	ds_read_b128 v[196:199], v242 offset:34816
	ds_read_b128 v[200:203], v242 offset:35840
	ds_read_b128 v[204:207], v242 offset:36864
	ds_read_b128 v[208:211], v242 offset:37888
	ds_read_b128 v[212:215], v242 offset:38912
	ds_read_b128 v[216:219], v242 offset:39936
	global_load_lds_dwordx4 v[238:239], off
	v_lshl_add_u64 v[238:239], s[2:3], 0, v[152:153]
	s_mov_b32 m0, s16
	s_nop 0
	global_load_lds_dwordx4 v[238:239], off
	s_waitcnt vmcnt(8) lgkmcnt(0)
	s_barrier
	v_mfma_f32_16x16x32_bf16 v[124:127], v[128:131], v[188:191], v[124:127]
	v_mfma_f32_16x16x32_bf16 v[120:123], v[136:139], v[188:191], v[120:123]
	v_mfma_f32_16x16x32_bf16 v[108:111], v[128:131], v[196:199], v[108:111]
	v_mfma_f32_16x16x32_bf16 v[104:107], v[136:139], v[196:199], v[104:107]
	v_mfma_f32_16x16x32_bf16 v[92:95], v[128:131], v[204:207], v[92:95]
	v_mfma_f32_16x16x32_bf16 v[88:91], v[136:139], v[204:207], v[88:91]
	v_mfma_f32_16x16x32_bf16 v[76:79], v[128:131], v[212:215], v[76:79]
	v_mfma_f32_16x16x32_bf16 v[72:75], v[136:139], v[212:215], v[72:75]
	v_mfma_f32_16x16x32_bf16 v[124:127], v[132:135], v[192:195], v[124:127]
	v_mfma_f32_16x16x32_bf16 v[120:123], v[140:143], v[192:195], v[120:123]
	v_mfma_f32_16x16x32_bf16 v[108:111], v[132:135], v[200:203], v[108:111]
	v_mfma_f32_16x16x32_bf16 v[104:107], v[140:143], v[200:203], v[104:107]
	v_mfma_f32_16x16x32_bf16 v[92:95], v[132:135], v[208:211], v[92:95]
	v_mfma_f32_16x16x32_bf16 v[88:91], v[140:143], v[208:211], v[88:91]
	v_mfma_f32_16x16x32_bf16 v[76:79], v[132:135], v[216:219], v[76:79]
	v_mfma_f32_16x16x32_bf16 v[72:75], v[140:143], v[216:219], v[72:75]
	v_mfma_f32_16x16x32_bf16 v[116:119], v[166:169], v[188:191], v[116:119]
	v_mfma_f32_16x16x32_bf16 v[112:115], v[180:183], v[188:191], v[112:115]
	v_mfma_f32_16x16x32_bf16 v[100:103], v[166:169], v[196:199], v[100:103]
	v_mfma_f32_16x16x32_bf16 v[96:99], v[180:183], v[196:199], v[96:99]
	v_mfma_f32_16x16x32_bf16 v[84:87], v[166:169], v[204:207], v[84:87]
	v_mfma_f32_16x16x32_bf16 v[80:83], v[180:183], v[204:207], v[80:83]
	v_mfma_f32_16x16x32_bf16 v[68:71], v[166:169], v[212:215], v[68:71]
	v_mfma_f32_16x16x32_bf16 v[64:67], v[180:183], v[212:215], v[64:67]
	v_mfma_f32_16x16x32_bf16 v[116:119], v[176:179], v[192:195], v[116:119]
	v_mfma_f32_16x16x32_bf16 v[112:115], v[184:187], v[192:195], v[112:115]
	v_mfma_f32_16x16x32_bf16 v[100:103], v[176:179], v[200:203], v[100:103]
	v_mfma_f32_16x16x32_bf16 v[96:99], v[184:187], v[200:203], v[96:99]
	v_mfma_f32_16x16x32_bf16 v[84:87], v[176:179], v[208:211], v[84:87]
	v_mfma_f32_16x16x32_bf16 v[80:83], v[184:187], v[208:211], v[80:83]
	v_mfma_f32_16x16x32_bf16 v[68:71], v[176:179], v[216:219], v[68:71]
	v_mfma_f32_16x16x32_bf16 v[64:67], v[184:187], v[216:219], v[64:67]
	s_barrier
	s_add_i32 s2, s82, s36
	v_lshl_add_u64 v[170:171], v[170:171], 0, s[30:31]
	s_mov_b32 m0, s2
	ds_read_b128 v[188:191], v242 offset:49152
	ds_read_b128 v[192:195], v242 offset:50176
	ds_read_b128 v[196:199], v242 offset:51200
	ds_read_b128 v[200:203], v242 offset:52224
	ds_read_b128 v[204:207], v242 offset:53248
	ds_read_b128 v[208:211], v242 offset:54272
	ds_read_b128 v[212:215], v242 offset:55296
	ds_read_b128 v[216:219], v242 offset:56320
	global_load_lds_dwordx4 v[170:171], off
	v_lshl_add_u64 v[170:171], v[232:233], 0, s[30:31]
	s_add_i32 m0, s2, 0x2000
	s_add_i32 s2, s83, s36
	global_load_lds_dwordx4 v[170:171], off
	v_lshl_add_u64 v[170:171], v[234:235], 0, s[30:31]
	s_mov_b32 m0, s2
	s_nop 0
	global_load_lds_dwordx4 v[170:171], off
	v_lshl_add_u64 v[170:171], v[246:247], 0, s[30:31]
	s_add_i32 m0, s2, 0x2000
	s_nop 0
	global_load_lds_dwordx4 v[170:171], off
	v_lshl_add_u64 v[170:171], v[248:249], 0, s[30:31]
	s_mov_b32 m0, s63
	s_nop 0
	global_load_lds_dwordx4 v[170:171], off
	v_lshl_add_u64 v[170:171], v[250:251], 0, s[30:31]
	s_mov_b32 m0, s18
	s_nop 0
	global_load_lds_dwordx4 v[170:171], off
	s_waitcnt vmcnt(8) lgkmcnt(0)
	s_barrier
	v_mfma_f32_16x16x32_bf16 v[60:63], v[128:131], v[188:191], v[60:63]
	v_mfma_f32_16x16x32_bf16 v[56:59], v[136:139], v[188:191], v[56:59]
	v_mfma_f32_16x16x32_bf16 v[44:47], v[128:131], v[196:199], v[44:47]
	v_mfma_f32_16x16x32_bf16 v[40:43], v[136:139], v[196:199], v[40:43]
	v_mfma_f32_16x16x32_bf16 v[28:31], v[128:131], v[204:207], v[28:31]
	v_mfma_f32_16x16x32_bf16 v[24:27], v[136:139], v[204:207], v[24:27]
	v_mfma_f32_16x16x32_bf16 v[12:15], v[128:131], v[212:215], v[12:15]
	v_mfma_f32_16x16x32_bf16 v[8:11], v[136:139], v[212:215], v[8:11]
	v_mfma_f32_16x16x32_bf16 v[60:63], v[132:135], v[192:195], v[60:63]
	v_mfma_f32_16x16x32_bf16 v[56:59], v[140:143], v[192:195], v[56:59]
	v_mfma_f32_16x16x32_bf16 v[44:47], v[132:135], v[200:203], v[44:47]
	v_mfma_f32_16x16x32_bf16 v[40:43], v[140:143], v[200:203], v[40:43]
	v_mfma_f32_16x16x32_bf16 v[28:31], v[132:135], v[208:211], v[28:31]
	v_mfma_f32_16x16x32_bf16 v[24:27], v[140:143], v[208:211], v[24:27]
	v_mfma_f32_16x16x32_bf16 v[12:15], v[132:135], v[216:219], v[12:15]
	v_mfma_f32_16x16x32_bf16 v[8:11], v[140:143], v[216:219], v[8:11]
	v_mfma_f32_16x16x32_bf16 v[52:55], v[166:169], v[188:191], v[52:55]
	v_mfma_f32_16x16x32_bf16 v[48:51], v[180:183], v[188:191], v[48:51]
	v_mfma_f32_16x16x32_bf16 v[36:39], v[166:169], v[196:199], v[36:39]
	v_mfma_f32_16x16x32_bf16 v[32:35], v[180:183], v[196:199], v[32:35]
	v_mfma_f32_16x16x32_bf16 v[20:23], v[166:169], v[204:207], v[20:23]
	v_mfma_f32_16x16x32_bf16 v[16:19], v[180:183], v[204:207], v[16:19]
	v_mfma_f32_16x16x32_bf16 v[4:7], v[166:169], v[212:215], v[4:7]
	v_mfma_f32_16x16x32_bf16 v[0:3], v[180:183], v[212:215], v[0:3]
	v_mfma_f32_16x16x32_bf16 v[52:55], v[176:179], v[192:195], v[52:55]
	v_mfma_f32_16x16x32_bf16 v[48:51], v[184:187], v[192:195], v[48:51]
	v_mfma_f32_16x16x32_bf16 v[36:39], v[176:179], v[200:203], v[36:39]
	v_mfma_f32_16x16x32_bf16 v[32:35], v[184:187], v[200:203], v[32:35]
	v_mfma_f32_16x16x32_bf16 v[20:23], v[176:179], v[208:211], v[20:23]
	v_mfma_f32_16x16x32_bf16 v[16:19], v[184:187], v[208:211], v[16:19]
	v_mfma_f32_16x16x32_bf16 v[4:7], v[176:179], v[216:219], v[4:7]
	v_mfma_f32_16x16x32_bf16 v[0:3], v[184:187], v[216:219], v[0:3]
	s_barrier
	s_add_u32 s0, s0, 0x100
	s_addc_u32 s1, s1, 0
	s_add_u32 s11, s11, 0x100
	s_addc_u32 s24, s24, 0
	s_cmp_ge_u32 s90, s60
	s_mov_b32 s2, s90
	s_cbranch_scc0 .LBB0_295
	s_branch .LBB0_297

.LBB0_297:
	s_setprio 0
	v_readlane_b32 s0, v255, 33
	v_readlane_b32 s1, v255, 34
	s_and_b64 vcc, exec, s[0:1]
	s_cbranch_vccz .LBB0_299
	s_barrier
